# attention: 16 bias lookups per head batched behind one LDS wait (on top of the conv and priority edits)
# speedup vs baseline: 1.0063x; 1.0027x over previous
; __device__ __forceinline__ void attn_unit2(const bf16* proj, bf16* yatt, const float* relb, unsigned char* lds, int unit) {
;     ...
;         {
;             f32x4 s[4];
; #pragma unroll
;             for (int kh = 0; kh < 2; ++kh) {
;                 bf16x8 kf[2][4];
; #pragma unroll
;                 for (int k2 = 0; k2 < 2; ++k2)
; #pragma unroll
;                     for (int ks = 0; ks < 4; ++ks) kf[k2][ks] = *(const bf16x8*)(Ks + (0 * 64 + (2 * kh + k2) * 16 + ql) * 136 + ks * 32 + g * 8);
;                 __builtin_amdgcn_sched_barrier(0);
;                 s[2 * kh] = (f32x4){0.f, 0.f, 0.f, 0.f}; s[2 * kh + 1] = (f32x4){0.f, 0.f, 0.f, 0.f};
; #pragma unroll
;                 for (int ks = 0; ks < 4; ++ks)
; #pragma unroll
;                     for (int k2 = 0; k2 < 2; ++k2) s[2 * kh + k2] = __builtin_amdgcn_mfma_f32_16x16x32_bf16(kf[k2][ks], Qb[0][ks], s[2 * kh + k2], 0, 0, 0);
;                 __builtin_amdgcn_sched_barrier(0);
;             }
;             float mx = -1e30f;
; #pragma unroll
;             for (int kt = 0; kt < 4; ++kt)
; #pragma unroll
;                 for (int r = 0; r < 4; ++r) {
;                     int rel = relbase - (kt * 16 + g * 4 + r); rel = rel > 256 ? 256 : rel; rel = rel < -256 ? -256 : rel;
;                     const float v = masked ? -1e30f : (s[kt][r] * LOG2E + bs[0 * 516 + rel + 256]);
;                     s[kt][r] = v; mx = fmaxf(mx, v);
;                 }
.LBB0_293:
	ds_read_b128 v[128:131], v176
	ds_read_b128 v[132:135], v176 offset:64
	ds_read_b128 v[136:139], v176 offset:128
	ds_read_b128 v[140:143], v176 offset:192
	ds_read_b128 v[182:185], v176 offset:4352
	ds_read_b128 v[198:201], v176 offset:4416
	ds_read_b128 v[202:205], v176 offset:4480
	ds_read_b128 v[206:209], v176 offset:4544
	v_cmp_le_i32_e32 vcc, v157, v149
	s_waitcnt lgkmcnt(7)
	v_mfma_f32_16x16x32_bf16 v[128:131], v[128:131], v[8:11], 0
	s_waitcnt lgkmcnt(3)
	v_mfma_f32_16x16x32_bf16 v[182:185], v[182:185], v[8:11], 0
	v_mfma_f32_16x16x32_bf16 v[128:131], v[132:135], v[0:3], v[128:131]
	s_waitcnt lgkmcnt(2)
	v_mfma_f32_16x16x32_bf16 v[132:135], v[198:201], v[0:3], v[182:185]
	v_mfma_f32_16x16x32_bf16 v[128:131], v[136:139], v[4:7], v[128:131]
	s_waitcnt lgkmcnt(1)
	v_mfma_f32_16x16x32_bf16 v[132:135], v[202:205], v[4:7], v[132:135]
	v_mfma_f32_16x16x32_bf16 v[140:143], v[140:143], v[12:15], v[128:131]
	s_waitcnt lgkmcnt(0)
	v_mfma_f32_16x16x32_bf16 v[136:139], v[206:209], v[12:15], v[132:135]
	s_nop 2
	ds_read_b128 v[128:131], v176 offset:8704
	s_nop 0
	ds_read_b128 v[132:135], v176 offset:8768
	ds_read_b128 v[182:185], v176 offset:8832
	ds_read_b128 v[198:201], v176 offset:8896
	ds_read_b128 v[202:205], v176 offset:13056
	ds_read_b128 v[206:209], v176 offset:13120
	ds_read_b128 v[210:213], v176 offset:13184
	ds_read_b128 v[214:217], v176 offset:13248
	s_waitcnt lgkmcnt(7)
	v_mfma_f32_16x16x32_bf16 v[128:131], v[128:131], v[8:11], 0
	s_waitcnt lgkmcnt(3)
	v_mfma_f32_16x16x32_bf16 v[202:205], v[202:205], v[8:11], 0
	v_mfma_f32_16x16x32_bf16 v[128:131], v[132:135], v[0:3], v[128:131]
	s_waitcnt lgkmcnt(2)
	v_mfma_f32_16x16x32_bf16 v[132:135], v[206:209], v[0:3], v[202:205]
	v_mfma_f32_16x16x32_bf16 v[128:131], v[182:185], v[4:7], v[128:131]
	s_waitcnt lgkmcnt(1)
	v_mfma_f32_16x16x32_bf16 v[182:185], v[210:213], v[4:7], v[132:135]
	v_mfma_f32_16x16x32_bf16 v[132:135], v[198:201], v[12:15], v[128:131]
	s_waitcnt lgkmcnt(0)
	v_mfma_f32_16x16x32_bf16 v[128:131], v[214:217], v[12:15], v[182:185]
	v_cmp_ge_i32_e64 s[8:9], v157, v159
	s_and_b64 s[8:9], s[8:9], vcc
	v_mov_b32_e32 v228, 0xf149f2ca
	s_nop 1
	v_med3_i32 v182, v167, s87, v237
	v_lshl_add_u32 v229, v182, 2, s90
	ds_read_b32 v212, v229 offset:1024
	v_subrev_u32_e32 v231, 1, v167
	v_med3_i32 v183, v231, s87, v237
	v_lshl_add_u32 v229, v183, 2, s90
	ds_read_b32 v213, v229 offset:1024
	v_subrev_u32_e32 v231, 2, v167
	v_med3_i32 v185, v231, s87, v237
	v_lshl_add_u32 v229, v185, 2, s90
	ds_read_b32 v214, v229 offset:1024
	v_subrev_u32_e32 v231, 3, v167
	v_med3_i32 v186, v231, s87, v237
	v_lshl_add_u32 v229, v186, 2, s90
	ds_read_b32 v215, v229 offset:1024
	v_subrev_u32_e32 v231, 16, v167
	v_med3_i32 v187, v231, s87, v237
	v_lshl_add_u32 v229, v187, 2, s90
	ds_read_b32 v216, v229 offset:1024
	v_subrev_u32_e32 v231, 17, v167
	v_med3_i32 v198, v231, s87, v237
	v_lshl_add_u32 v229, v198, 2, s90
	ds_read_b32 v217, v229 offset:1024
	v_subrev_u32_e32 v231, 18, v167
	v_med3_i32 v199, v231, s87, v237
	v_lshl_add_u32 v229, v199, 2, s90
	ds_read_b32 v218, v229 offset:1024
	v_subrev_u32_e32 v231, 19, v167
	v_med3_i32 v200, v231, s87, v237
	v_lshl_add_u32 v229, v200, 2, s90
	ds_read_b32 v219, v229 offset:1024
	v_subrev_u32_e32 v231, 32, v167
	v_med3_i32 v201, v231, s87, v237
	v_lshl_add_u32 v229, v201, 2, s90
	ds_read_b32 v220, v229 offset:1024
	v_subrev_u32_e32 v231, 33, v167
	v_med3_i32 v202, v231, s87, v237
	v_lshl_add_u32 v229, v202, 2, s90
	ds_read_b32 v221, v229 offset:1024
	v_subrev_u32_e32 v231, 34, v167
	v_med3_i32 v203, v231, s87, v237
	v_lshl_add_u32 v229, v203, 2, s90
	ds_read_b32 v222, v229 offset:1024
	v_subrev_u32_e32 v231, 35, v167
	v_med3_i32 v204, v231, s87, v237
	v_lshl_add_u32 v229, v204, 2, s90
	ds_read_b32 v223, v229 offset:1024
	v_subrev_u32_e32 v231, 48, v167
	v_med3_i32 v205, v231, s87, v237
	v_lshl_add_u32 v229, v205, 2, s90
	ds_read_b32 v224, v229 offset:1024
	v_subrev_u32_e32 v231, 49, v167
	v_med3_i32 v206, v231, s87, v237
	v_lshl_add_u32 v229, v206, 2, s90
	ds_read_b32 v225, v229 offset:1024
	v_subrev_u32_e32 v231, 50, v167
	v_med3_i32 v207, v231, s87, v237
	v_lshl_add_u32 v229, v207, 2, s90
	ds_read_b32 v226, v229 offset:1024
	v_subrev_u32_e32 v231, 51, v167
	v_med3_i32 v208, v231, s87, v237
	v_lshl_add_u32 v229, v208, 2, s90
	ds_read_b32 v227, v229 offset:1024
	s_waitcnt lgkmcnt(0)
	v_fmac_f32_e32 v212, 0x3fb8aa3b, v140
	v_fmac_f32_e32 v213, 0x3fb8aa3b, v141
	v_fmac_f32_e32 v214, 0x3fb8aa3b, v142
	v_fmac_f32_e32 v215, 0x3fb8aa3b, v143
	v_fmac_f32_e32 v216, 0x3fb8aa3b, v136
	v_fmac_f32_e32 v217, 0x3fb8aa3b, v137
	v_fmac_f32_e32 v218, 0x3fb8aa3b, v138
	v_fmac_f32_e32 v219, 0x3fb8aa3b, v139
	v_fmac_f32_e32 v220, 0x3fb8aa3b, v132
	v_fmac_f32_e32 v221, 0x3fb8aa3b, v133
	v_fmac_f32_e32 v222, 0x3fb8aa3b, v134
	v_fmac_f32_e32 v223, 0x3fb8aa3b, v135
	v_fmac_f32_e32 v224, 0x3fb8aa3b, v128
	v_fmac_f32_e32 v225, 0x3fb8aa3b, v129
	v_fmac_f32_e32 v226, 0x3fb8aa3b, v130
	v_fmac_f32_e32 v227, 0x3fb8aa3b, v131
	v_cndmask_b32_e64 v210, v228, v212, s[8:9]
	v_cndmask_b32_e64 v209, v228, v213, s[8:9]
	v_cndmask_b32_e64 v211, v228, v214, s[8:9]
	v_cndmask_b32_e64 v141, v228, v215, s[8:9]
	v_cndmask_b32_e64 v142, v228, v216, s[8:9]
	v_cndmask_b32_e64 v140, v228, v217, s[8:9]
	v_cndmask_b32_e64 v137, v228, v218, s[8:9]
	v_cndmask_b32_e64 v136, v228, v219, s[8:9]
	v_cndmask_b32_e64 v139, v228, v220, s[8:9]
	v_cndmask_b32_e64 v138, v228, v221, s[8:9]
	v_cndmask_b32_e64 v133, v228, v222, s[8:9]
	v_cndmask_b32_e64 v132, v228, v223, s[8:9]
	v_cndmask_b32_e64 v135, v228, v224, s[8:9]
	v_cndmask_b32_e64 v134, v228, v225, s[8:9]
	v_cndmask_b32_e64 v129, v228, v226, s[8:9]
	v_cndmask_b32_e64 v128, v228, v227, s[8:9]
	v_mov_b32_e32 v184, 0xf149f2ca
	v_max3_f32 v130, v210, v184, v209
	v_max3_f32 v130, v130, v211, v141
	v_max3_f32 v130, v130, v142, v140
	v_max3_f32 v130, v130, v137, v136
	v_max3_f32 v130, v130, v139, v138
	v_max3_f32 v130, v130, v133, v132
	v_max3_f32 v130, v130, v135, v134
	v_max3_f32 v130, v130, v129, v128
	ds_bpermute_b32 v131, v160, v130
	s_waitcnt lgkmcnt(0)
; __device__ __forceinline__ void attn_unit2(const bf16* proj, bf16* yatt, const float* relb, unsigned char* lds, int unit) {
;     ...
;             mx = fmaxf(mx, __shfl_xor(mx, 16)); mx = fmaxf(mx, __shfl_xor(mx, 32));
;             const float m_new = fmaxf(m_run[0], mx), alpha = __builtin_amdgcn_exp2f(m_run[0] - m_new);
;             float ps = 0.f;
; #pragma unroll
;             for (int kt = 0; kt < 4; ++kt)
; #pragma unroll
;                 for (int r = 0; r < 4; ++r) { const float pv = __builtin_amdgcn_exp2f(s[kt][r] - m_new); s[kt][r] = pv; ps += pv; }
;             ps += __shfl_xor(ps, 16); ps += __shfl_xor(ps, 32);
;             l_run[0] = l_run[0] * alpha + ps; m_run[0] = m_new;
; #pragma unroll
;             for (int dt = 0; dt < 8; ++dt) O[0][dt] = O[0][dt] * alpha;
;             bf16x8 pb[2];
; #pragma unroll
;             for (int j = 0; j < 2; ++j) {
;                 u32x4 wv; wv.x = pk2(s[2 * j][0], s[2 * j][1]); wv.y = pk2(s[2 * j][2], s[2 * j][3]); wv.z = pk2(s[2 * j + 1][0], s[2 * j + 1][1]); wv.w = pk2(s[2 * j + 1][2], s[2 * j + 1][3]);
;                 pb[j] = __builtin_bit_cast(bf16x8, wv);
;             }
;             { const unsigned vaddr = vbase + (unsigned)((0 * 64) * 144 * 2);
;               { u32x2 lo[4][2], hi[4][2];
;                 asm volatile("ds_read_b64_tr_b16 %0, %1 offset:0" : "=v"(lo[0][0]) : "v"(vaddr) : "memory");
;                 asm volatile("ds_read_b64_tr_b16 %0, %1 offset:4608" : "=v"(hi[0][0]) : "v"(vaddr) : "memory");
;                 asm volatile("ds_read_b64_tr_b16 %0, %1 offset:9216" : "=v"(lo[0][1]) : "v"(vaddr) : "memory");
;                 asm volatile("ds_read_b64_tr_b16 %0, %1 offset:13824" : "=v"(hi[0][1]) : "v"(vaddr) : "memory");
;                 asm volatile("ds_read_b64_tr_b16 %0, %1 offset:32" : "=v"(lo[1][0]) : "v"(vaddr) : "memory");
;                 asm volatile("ds_read_b64_tr_b16 %0, %1 offset:4640" : "=v"(hi[1][0]) : "v"(vaddr) : "memory");
;                 asm volatile("ds_read_b64_tr_b16 %0, %1 offset:9248" : "=v"(lo[1][1]) : "v"(vaddr) : "memory");
;                 asm volatile("ds_read_b64_tr_b16 %0, %1 offset:13856" : "=v"(hi[1][1]) : "v"(vaddr) : "memory");
;                 asm volatile("ds_read_b64_tr_b16 %0, %1 offset:64" : "=v"(lo[2][0]) : "v"(vaddr) : "memory");
;                 asm volatile("ds_read_b64_tr_b16 %0, %1 offset:4672" : "=v"(hi[2][0]) : "v"(vaddr) : "memory");
	v_max_f32_e32 v131, v131, v131
	v_max_f32_e32 v130, v130, v131
	ds_bpermute_b32 v131, v161, v130
	s_waitcnt lgkmcnt(0)
	v_max3_f32 v179, v154, v130, v131
	v_sub_f32_e32 v131, v210, v179
	v_sub_f32_e32 v130, v154, v179
	v_exp_f32_e32 v131, v131
	v_sub_f32_e32 v154, v209, v179
	v_exp_f32_e32 v194, v154
	v_sub_f32_e32 v154, v211, v179
	v_exp_f32_e32 v195, v154
	v_sub_f32_e32 v141, v141, v179
	v_exp_f32_e32 v141, v141
	v_sub_f32_e32 v142, v142, v179
	v_add_f32_e32 v143, 0, v131
	v_exp_f32_e32 v142, v142
	v_sub_f32_e32 v140, v140, v179
	v_add_f32_e32 v143, v194, v143
	v_exp_f32_e32 v140, v140
	v_sub_f32_e32 v137, v137, v179
	v_add_f32_e32 v143, v195, v143
	v_exp_f32_e32 v137, v137
	v_sub_f32_e32 v136, v136, v179
	v_add_f32_e32 v143, v141, v143
	v_exp_f32_e32 v136, v136
	v_sub_f32_e32 v139, v139, v179
	v_add_f32_e32 v143, v142, v143
	v_exp_f32_e32 v139, v139
	v_sub_f32_e32 v138, v138, v179
	v_add_f32_e32 v143, v140, v143
	v_exp_f32_e32 v138, v138
	v_sub_f32_e32 v133, v133, v179
	v_add_f32_e32 v143, v137, v143
	v_exp_f32_e32 v133, v133
	v_sub_f32_e32 v132, v132, v179
	v_add_f32_e32 v143, v136, v143
	v_exp_f32_e32 v211, v132
	v_add_f32_e32 v143, v139, v143
	v_sub_f32_e32 v135, v135, v179
	v_add_f32_e32 v143, v138, v143
	v_exp_f32_e32 v135, v135
	v_sub_f32_e32 v134, v134, v179
	v_add_f32_e32 v143, v133, v143
	v_exp_f32_e32 v134, v134
	v_sub_f32_e32 v129, v129, v179
	v_add_f32_e32 v132, v211, v143
	v_exp_f32_e32 v143, v129
	v_sub_f32_e32 v128, v128, v179
	v_exp_f32_e32 v212, v128
	v_add_f32_e32 v132, v135, v132
	v_add_f32_e32 v132, v134, v132
	v_add_f32_e32 v129, v143, v132
	v_add_f32_e32 v128, v212, v129
	ds_bpermute_b32 v129, v160, v128
	v_cvt_pk_bf16_f32 v132, v139, v138
	v_exp_f32_e32 v154, v130
	v_cvt_pk_bf16_f32 v130, v142, v140
	v_cvt_pk_bf16_f32 v134, v135, v134
	s_waitcnt lgkmcnt(0)
	v_add_f32_e32 v209, v128, v129
	v_cvt_pk_bf16_f32 v128, v131, v194
	v_cvt_pk_bf16_f32 v131, v137, v136
	ds_read_b64_tr_b16 v[136:137], v158 offset:0
	ds_read_b64_tr_b16 v[138:139], v158 offset:4608
	v_cvt_pk_bf16_f32 v129, v195, v141
	ds_read_b64_tr_b16 v[140:141], v158 offset:9216
	v_cvt_pk_bf16_f32 v135, v143, v212
	ds_read_b64_tr_b16 v[142:143], v158 offset:13824
	ds_read_b64_tr_b16 v[212:213], v158 offset:32
	ds_read_b64_tr_b16 v[214:215], v158 offset:4640
	ds_read_b64_tr_b16 v[216:217], v158 offset:9248
	ds_read_b64_tr_b16 v[218:219], v158 offset:13856
	ds_read_b64_tr_b16 v[220:221], v158 offset:64
	ds_read_b64_tr_b16 v[222:223], v158 offset:4672
	ds_read_b64_tr_b16 v[224:225], v158 offset:9280
	ds_read_b64_tr_b16 v[226:227], v158 offset:13888
	ds_read_b64_tr_b16 v[238:239], v158 offset:96
	ds_read_b64_tr_b16 v[240:241], v158 offset:4704
	ds_read_b64_tr_b16 v[242:243], v158 offset:9312
	v_pk_mul_f32 v[90:91], v[90:91], v[154:155] op_sel_hi:[1,0]
	v_pk_mul_f32 v[88:89], v[88:89], v[154:155] op_sel_hi:[1,0]
	ds_read_b64_tr_b16 v[244:245], v158 offset:13920
	v_pk_mul_f32 v[94:95], v[94:95], v[154:155] op_sel_hi:[1,0]
	s_waitcnt lgkmcnt(0)
	v_pk_mul_f32 v[92:93], v[92:93], v[154:155] op_sel_hi:[1,0]
	v_mfma_f32_16x16x32_bf16 v[88:91], v[136:139], v[128:131], v[88:91]
	ds_read_b64_tr_b16 v[136:137], v158 offset:128
	ds_read_b64_tr_b16 v[138:139], v158 offset:4736
	v_cvt_pk_bf16_f32 v133, v133, v211
	v_mul_f32_e64 v102, v102, v154
	v_mul_f32_e64 v103, v103, v154
	v_mfma_f32_16x16x32_bf16 v[88:91], v[140:143], v[132:135], v[88:91]
	ds_read_b64_tr_b16 v[140:141], v158 offset:9344
	ds_read_b64_tr_b16 v[142:143], v158 offset:13952
	v_mul_f32_e64 v100, v100, v154
	v_mul_f32_e64 v101, v101, v154
	v_mfma_f32_16x16x32_bf16 v[92:95], v[212:215], v[128:131], v[92:95]
	ds_read_b64_tr_b16 v[212:213], v158 offset:160
	ds_read_b64_tr_b16 v[214:215], v158 offset:4768
	v_mul_f32_e64 v106, v106, v154
	v_mul_f32_e64 v107, v107, v154
	v_mfma_f32_16x16x32_bf16 v[92:95], v[216:219], v[132:135], v[92:95]
	ds_read_b64_tr_b16 v[216:217], v158 offset:9376
	ds_read_b64_tr_b16 v[218:219], v158 offset:13984
	v_mul_f32_e64 v104, v104, v154
	v_mul_f32_e64 v105, v105, v154
	v_mfma_f32_16x16x32_bf16 v[100:103], v[220:223], v[128:131], v[100:103]
	ds_read_b64_tr_b16 v[220:221], v158 offset:192
	ds_read_b64_tr_b16 v[222:223], v158 offset:4800
	v_mul_f32_e64 v114, v114, v154
	v_mul_f32_e64 v115, v115, v154
	v_mfma_f32_16x16x32_bf16 v[100:103], v[224:227], v[132:135], v[100:103]
	ds_read_b64_tr_b16 v[224:225], v158 offset:9408
	ds_read_b64_tr_b16 v[226:227], v158 offset:14016
	v_mul_f32_e64 v112, v112, v154
	v_mul_f32_e64 v113, v113, v154
	v_mfma_f32_16x16x32_bf16 v[104:107], v[238:241], v[128:131], v[104:107]
	ds_read_b64_tr_b16 v[238:239], v158 offset:224
	ds_read_b64_tr_b16 v[240:241], v158 offset:4832
	v_mul_f32_e64 v118, v118, v154
	v_mul_f32_e64 v119, v119, v154
	v_mfma_f32_16x16x32_bf16 v[104:107], v[242:245], v[132:135], v[104:107]
	ds_read_b64_tr_b16 v[242:243], v158 offset:9440
	v_mul_f32_e64 v116, v116, v154
	v_mul_f32_e64 v117, v117, v154
	v_pk_mul_f32 v[126:127], v[126:127], v[154:155] op_sel_hi:[1,0]
	v_pk_mul_f32 v[124:125], v[124:125], v[154:155] op_sel_hi:[1,0]
	v_pk_mul_f32 v[122:123], v[122:123], v[154:155] op_sel_hi:[1,0]
	v_pk_mul_f32 v[120:121], v[120:121], v[154:155] op_sel_hi:[1,0]
	ds_read_b64_tr_b16 v[244:245], v158 offset:14048
	ds_bpermute_b32 v210, v161, v209
	s_waitcnt lgkmcnt(0)
; __device__ __forceinline__ void attn_unit2(const bf16* proj, bf16* yatt, const float* relb, unsigned char* lds, int unit) {
;     ...
; #pragma unroll
;                 for (int d4 = 0; d4 < 4; ++d4)
; #pragma unroll
;                     for (int j = 0; j < 2; ++j) { u32x4 av; av.x = lo[d4][j].x; av.y = lo[d4][j].y; av.z = hi[d4][j].x; av.w = hi[d4][j].y;
;                         O[0][4 + d4] = __builtin_amdgcn_mfma_f32_16x16x32_bf16(__builtin_bit_cast(bf16x8, av), pb[j], O[0][4 + d4], 0, 0, 0); }
;     ...
;         {
;             f32x4 s[4];
; #pragma unroll
;             for (int kh = 0; kh < 2; ++kh) {
;                 bf16x8 kf[2][4];
; #pragma unroll
;                 for (int k2 = 0; k2 < 2; ++k2)
; #pragma unroll
;                     for (int ks = 0; ks < 4; ++ks) kf[k2][ks] = *(const bf16x8*)(Ks + (1 * 64 + (2 * kh + k2) * 16 + ql) * 136 + ks * 32 + g * 8);
;                 __builtin_amdgcn_sched_barrier(0);
;                 s[2 * kh] = (f32x4){0.f, 0.f, 0.f, 0.f}; s[2 * kh + 1] = (f32x4){0.f, 0.f, 0.f, 0.f};
; #pragma unroll
;                 for (int ks = 0; ks < 4; ++ks)
; #pragma unroll
;                     for (int k2 = 0; k2 < 2; ++k2) s[2 * kh + k2] = __builtin_amdgcn_mfma_f32_16x16x32_bf16(kf[k2][ks], Qb[1][ks], s[2 * kh + k2], 0, 0, 0);
;                 __builtin_amdgcn_sched_barrier(0);
;             }
;             float mx = -1e30f;
; #pragma unroll
;             for (int kt = 0; kt < 4; ++kt)
; #pragma unroll
;                 for (int r = 0; r < 4; ++r) {
;                     int rel = relbase - (kt * 16 + g * 4 + r); rel = rel > 256 ? 256 : rel; rel = rel < -256 ? -256 : rel;
;                     const float v = masked ? -1e30f : (s[kt][r] * LOG2E + bs[1 * 516 + rel + 256]);
;                     s[kt][r] = v; mx = fmaxf(mx, v);
;                 }
	s_nop 0
	v_mfma_f32_16x16x32_bf16 v[112:115], v[136:139], v[128:131], v[112:115]
	v_mfma_f32_16x16x32_bf16 v[116:119], v[212:215], v[128:131], v[116:119]
	v_mfma_f32_16x16x32_bf16 v[124:127], v[220:223], v[128:131], v[124:127]
	v_mfma_f32_16x16x32_bf16 v[120:123], v[238:241], v[128:131], v[120:123]
	v_mfma_f32_16x16x32_bf16 v[112:115], v[140:143], v[132:135], v[112:115]
	v_mfma_f32_16x16x32_bf16 v[116:119], v[216:219], v[132:135], v[116:119]
	v_mfma_f32_16x16x32_bf16 v[124:127], v[224:227], v[132:135], v[124:127]
	v_mfma_f32_16x16x32_bf16 v[120:123], v[242:245], v[132:135], v[120:123]
	ds_read_b128 v[128:131], v177 offset:17408
	ds_read_b128 v[132:135], v177 offset:17472
	ds_read_b128 v[136:139], v177 offset:17536
	ds_read_b128 v[140:143], v177 offset:17600
	ds_read_b128 v[212:215], v177 offset:21760
	ds_read_b128 v[216:219], v177 offset:21824
	ds_read_b128 v[220:223], v177 offset:21888
	ds_read_b128 v[224:227], v177 offset:21952
	s_waitcnt lgkmcnt(7)
	v_mfma_f32_16x16x32_bf16 v[128:131], v[128:131], v[24:27], 0
	s_waitcnt lgkmcnt(3)
	v_mfma_f32_16x16x32_bf16 v[212:215], v[212:215], v[24:27], 0
	v_mfma_f32_16x16x32_bf16 v[128:131], v[132:135], v[16:19], v[128:131]
	s_waitcnt lgkmcnt(2)
	v_mfma_f32_16x16x32_bf16 v[132:135], v[216:219], v[16:19], v[212:215]
	v_mfma_f32_16x16x32_bf16 v[128:131], v[136:139], v[20:23], v[128:131]
	s_waitcnt lgkmcnt(1)
	v_mfma_f32_16x16x32_bf16 v[132:135], v[220:223], v[20:23], v[132:135]
	v_mfma_f32_16x16x32_bf16 v[140:143], v[140:143], v[28:31], v[128:131]
	s_waitcnt lgkmcnt(0)
	v_mfma_f32_16x16x32_bf16 v[136:139], v[224:227], v[28:31], v[132:135]
	s_nop 2
	ds_read_b128 v[128:131], v177 offset:26112
	s_nop 0
	ds_read_b128 v[132:135], v177 offset:26176
	ds_read_b128 v[212:215], v177 offset:26240
	ds_read_b128 v[216:219], v177 offset:26304
	ds_read_b128 v[220:223], v177 offset:30464
	ds_read_b128 v[224:227], v177 offset:30528
	ds_read_b128 v[238:241], v177 offset:30592
	ds_read_b128 v[242:245], v177 offset:30656
	s_waitcnt lgkmcnt(7)
	v_mfma_f32_16x16x32_bf16 v[128:131], v[128:131], v[24:27], 0
	s_waitcnt lgkmcnt(3)
	v_mfma_f32_16x16x32_bf16 v[220:223], v[220:223], v[24:27], 0
	v_mfma_f32_16x16x32_bf16 v[128:131], v[132:135], v[16:19], v[128:131]
	s_waitcnt lgkmcnt(2)
	v_mfma_f32_16x16x32_bf16 v[132:135], v[224:227], v[16:19], v[220:223]
	v_mfma_f32_16x16x32_bf16 v[128:131], v[212:215], v[20:23], v[128:131]
	s_waitcnt lgkmcnt(1)
	v_mfma_f32_16x16x32_bf16 v[212:215], v[238:241], v[20:23], v[132:135]
	v_mfma_f32_16x16x32_bf16 v[132:135], v[216:219], v[28:31], v[128:131]
	s_waitcnt lgkmcnt(0)
	v_mfma_f32_16x16x32_bf16 v[128:131], v[242:245], v[28:31], v[212:215]
	v_mov_b32_e32 v228, 0xf149f2ca
	v_lshl_add_u32 v229, v182, 2, s90
	ds_read_b32 v220, v229 offset:3088
	v_lshl_add_u32 v229, v183, 2, s90
	ds_read_b32 v221, v229 offset:3088
	v_lshl_add_u32 v229, v185, 2, s90
	ds_read_b32 v222, v229 offset:3088
	v_lshl_add_u32 v229, v186, 2, s90
	ds_read_b32 v223, v229 offset:3088
	v_lshl_add_u32 v229, v187, 2, s90
	ds_read_b32 v224, v229 offset:3088
	v_lshl_add_u32 v229, v198, 2, s90
	ds_read_b32 v225, v229 offset:3088
	v_lshl_add_u32 v229, v199, 2, s90
	ds_read_b32 v226, v229 offset:3088
	v_lshl_add_u32 v229, v200, 2, s90
	ds_read_b32 v227, v229 offset:3088
	v_lshl_add_u32 v229, v201, 2, s90
	ds_read_b32 v246, v229 offset:3088
	v_lshl_add_u32 v229, v202, 2, s90
	ds_read_b32 v247, v229 offset:3088
	v_lshl_add_u32 v229, v203, 2, s90
	ds_read_b32 v248, v229 offset:3088
	v_lshl_add_u32 v229, v204, 2, s90
	ds_read_b32 v249, v229 offset:3088
	v_lshl_add_u32 v229, v205, 2, s90
	ds_read_b32 v250, v229 offset:3088
	v_lshl_add_u32 v229, v206, 2, s90
	ds_read_b32 v251, v229 offset:3088
	v_lshl_add_u32 v229, v207, 2, s90
	ds_read_b32 v252, v229 offset:3088
	v_lshl_add_u32 v229, v208, 2, s90
	ds_read_b32 v253, v229 offset:3088
	s_waitcnt lgkmcnt(0)
	v_fmac_f32_e32 v220, 0x3fb8aa3b, v140
	v_fmac_f32_e32 v221, 0x3fb8aa3b, v141
	v_fmac_f32_e32 v222, 0x3fb8aa3b, v142
	v_fmac_f32_e32 v223, 0x3fb8aa3b, v143
	v_fmac_f32_e32 v224, 0x3fb8aa3b, v136
	v_fmac_f32_e32 v225, 0x3fb8aa3b, v137
	v_fmac_f32_e32 v226, 0x3fb8aa3b, v138
	v_fmac_f32_e32 v227, 0x3fb8aa3b, v139
	v_fmac_f32_e32 v246, 0x3fb8aa3b, v132
	v_fmac_f32_e32 v247, 0x3fb8aa3b, v133
	v_fmac_f32_e32 v248, 0x3fb8aa3b, v134
	v_fmac_f32_e32 v249, 0x3fb8aa3b, v135
	v_fmac_f32_e32 v250, 0x3fb8aa3b, v128
	v_fmac_f32_e32 v251, 0x3fb8aa3b, v129
	v_fmac_f32_e32 v252, 0x3fb8aa3b, v130
	v_fmac_f32_e32 v253, 0x3fb8aa3b, v131
	v_cndmask_b32_e64 v211, v228, v220, s[8:9]
	v_cndmask_b32_e64 v184, v228, v221, s[8:9]
	v_cndmask_b32_e64 v182, v228, v222, s[8:9]
	v_cndmask_b32_e64 v141, v228, v223, s[8:9]
	v_cndmask_b32_e64 v183, v228, v224, s[8:9]
	v_cndmask_b32_e64 v140, v228, v225, s[8:9]
	v_cndmask_b32_e64 v143, v228, v226, s[8:9]
	v_cndmask_b32_e64 v142, v228, v227, s[8:9]
	v_cndmask_b32_e64 v139, v228, v246, s[8:9]
	v_cndmask_b32_e64 v138, v228, v247, s[8:9]
	v_cndmask_b32_e64 v133, v228, v248, s[8:9]
	v_cndmask_b32_e64 v132, v228, v249, s[8:9]
	v_cndmask_b32_e64 v135, v228, v250, s[8:9]
	v_cndmask_b32_e64 v134, v228, v251, s[8:9]
	v_cndmask_b32_e64 v129, v228, v252, s[8:9]
	v_cndmask_b32_e64 v128, v228, v253, s[8:9]
	s_mov_b32 s8, 0xf149f2ca
	v_max3_f32 v130, v211, s8, v184
	v_max3_f32 v130, v130, v182, v141
	v_max3_f32 v130, v130, v183, v140
	v_max3_f32 v130, v130, v143, v142
	v_max3_f32 v130, v130, v139, v138
	v_max3_f32 v130, v130, v133, v132
	v_max3_f32 v130, v130, v135, v134
	v_max3_f32 v130, v130, v129, v128
	ds_bpermute_b32 v131, v160, v130
	v_add_f32_e32 v136, v209, v210
	v_fmac_f32_e32 v136, v181, v154
	v_add_u32_e32 v157, 1, v157
	v_add_u32_e32 v163, 64, v163
	s_waitcnt lgkmcnt(0)
; __device__ __forceinline__ void attn_unit2(const bf16* proj, bf16* yatt, const float* relb, unsigned char* lds, int unit) {
;     ...
;             mx = fmaxf(mx, __shfl_xor(mx, 16)); mx = fmaxf(mx, __shfl_xor(mx, 32));
;             const float m_new = fmaxf(m_run[1], mx), alpha = __builtin_amdgcn_exp2f(m_run[1] - m_new);
;             float ps = 0.f;
; #pragma unroll
;             for (int kt = 0; kt < 4; ++kt)
; #pragma unroll
;                 for (int r = 0; r < 4; ++r) { const float pv = __builtin_amdgcn_exp2f(s[kt][r] - m_new); s[kt][r] = pv; ps += pv; }
;             ps += __shfl_xor(ps, 16); ps += __shfl_xor(ps, 32);
;             l_run[1] = l_run[1] * alpha + ps; m_run[1] = m_new;
; #pragma unroll
;             for (int dt = 0; dt < 8; ++dt) O[1][dt] = O[1][dt] * alpha;
;             bf16x8 pb[2];
; #pragma unroll
;             for (int j = 0; j < 2; ++j) {
;                 u32x4 wv; wv.x = pk2(s[2 * j][0], s[2 * j][1]); wv.y = pk2(s[2 * j][2], s[2 * j][3]); wv.z = pk2(s[2 * j + 1][0], s[2 * j + 1][1]); wv.w = pk2(s[2 * j + 1][2], s[2 * j + 1][3]);
;                 pb[j] = __builtin_bit_cast(bf16x8, wv);
;             }
;             { const unsigned vaddr = vbase + (unsigned)((1 * 64) * 144 * 2);
;               { u32x2 lo[4][2], hi[4][2];
;                 asm volatile("ds_read_b64_tr_b16 %0, %1 offset:0" : "=v"(lo[0][0]) : "v"(vaddr) : "memory");
;                 asm volatile("ds_read_b64_tr_b16 %0, %1 offset:4608" : "=v"(hi[0][0]) : "v"(vaddr) : "memory");
;                 asm volatile("ds_read_b64_tr_b16 %0, %1 offset:9216" : "=v"(lo[0][1]) : "v"(vaddr) : "memory");
;                 asm volatile("ds_read_b64_tr_b16 %0, %1 offset:13824" : "=v"(hi[0][1]) : "v"(vaddr) : "memory");
;                 asm volatile("ds_read_b64_tr_b16 %0, %1 offset:32" : "=v"(lo[1][0]) : "v"(vaddr) : "memory");
;                 asm volatile("ds_read_b64_tr_b16 %0, %1 offset:4640" : "=v"(hi[1][0]) : "v"(vaddr) : "memory");
;                 asm volatile("ds_read_b64_tr_b16 %0, %1 offset:9248" : "=v"(lo[1][1]) : "v"(vaddr) : "memory");
;                 asm volatile("ds_read_b64_tr_b16 %0, %1 offset:13856" : "=v"(hi[1][1]) : "v"(vaddr) : "memory");
;                 asm volatile("ds_read_b64_tr_b16 %0, %1 offset:64" : "=v"(lo[2][0]) : "v"(vaddr) : "memory");
;                 asm volatile("ds_read_b64_tr_b16 %0, %1 offset:4672" : "=v"(hi[2][0]) : "v"(vaddr) : "memory");
	v_max_f32_e32 v131, v131, v131
	v_max_f32_e32 v130, v130, v131
	ds_bpermute_b32 v131, v161, v130
	v_add_u32_e32 v164, 64, v164
	v_add_u32_e32 v165, 64, v165
	v_add_u32_e32 v166, 64, v166
	v_subrev_u32_e32 v167, 64, v167
	s_waitcnt lgkmcnt(0)
	v_max3_f32 v137, v180, v130, v131
	v_sub_f32_e32 v131, v211, v137
	v_sub_f32_e32 v130, v180, v137
	v_exp_f32_e32 v131, v131
	v_sub_f32_e32 v180, v184, v137
	v_exp_f32_e32 v180, v180
	v_sub_f32_e32 v181, v182, v137
	v_exp_f32_e32 v181, v181
	v_sub_f32_e32 v141, v141, v137
	v_exp_f32_e32 v141, v141
	v_sub_f32_e32 v182, v183, v137
	v_add_f32_e32 v154, 0, v131
	v_exp_f32_e32 v182, v182
	v_sub_f32_e32 v140, v140, v137
	v_add_f32_e32 v154, v180, v154
	v_exp_f32_e32 v140, v140
	v_sub_f32_e32 v143, v143, v137
	v_add_f32_e32 v154, v181, v154
	v_exp_f32_e32 v143, v143
	v_sub_f32_e32 v142, v142, v137
	v_add_f32_e32 v154, v141, v154
	v_exp_f32_e32 v142, v142
	v_sub_f32_e32 v139, v139, v137
	v_add_f32_e32 v154, v182, v154
	v_exp_f32_e32 v139, v139
	v_sub_f32_e32 v138, v138, v137
	v_add_f32_e32 v154, v140, v154
	v_exp_f32_e32 v183, v138
	v_add_f32_e32 v154, v143, v154
	v_add_f32_e32 v154, v142, v154
	v_add_f32_e32 v154, v139, v154
	v_sub_f32_e32 v133, v133, v137
	v_add_f32_e32 v138, v183, v154
	v_exp_f32_e32 v154, v133
	v_sub_f32_e32 v132, v132, v137
	v_exp_f32_e32 v184, v132
	v_sub_f32_e32 v129, v129, v137
	v_add_f32_e32 v133, v154, v138
	v_exp_f32_e32 v187, v129
	v_add_f32_e32 v132, v184, v133
	v_sub_f32_e32 v133, v135, v137
	v_exp_f32_e32 v185, v133
	v_sub_f32_e32 v133, v134, v137
	v_exp_f32_e32 v186, v133
	v_sub_f32_e32 v128, v128, v137
	v_exp_f32_e32 v194, v128
	v_add_f32_e32 v132, v185, v132
	v_add_f32_e32 v132, v186, v132
	v_add_f32_e32 v129, v187, v132
	v_add_f32_e32 v129, v194, v129
	v_exp_f32_e32 v128, v130
	ds_bpermute_b32 v130, v160, v129
	v_cvt_pk_bf16_f32 v133, v181, v141
	v_cvt_pk_bf16_f32 v134, v182, v140
	ds_read_b64_tr_b16 v[140:141], v162 offset:0
	v_cvt_pk_bf16_f32 v135, v143, v142
	s_waitcnt lgkmcnt(0)
	v_add_f32_e32 v129, v129, v130
	ds_bpermute_b32 v130, v161, v129
	ds_read_b64_tr_b16 v[142:143], v162 offset:4608
	v_cvt_pk_bf16_f32 v132, v131, v180
	ds_read_b64_tr_b16 v[180:181], v162 offset:9216
	v_pk_mul_f32 v[66:67], v[66:67], v[128:129] op_sel_hi:[1,0]
	s_waitcnt lgkmcnt(0)
	v_add_f32_e32 v138, v129, v130
	v_fmac_f32_e32 v138, v178, v128
	v_pk_mul_f32 v[64:65], v[64:65], v[128:129] op_sel_hi:[1,0]
	v_pk_mul_f32 v[70:71], v[70:71], v[128:129] op_sel_hi:[1,0]
	v_pk_mul_f32 v[68:69], v[68:69], v[128:129] op_sel_hi:[1,0]
	v_pk_mul_f32 v[74:75], v[74:75], v[128:129] op_sel_hi:[1,0]
	v_pk_mul_f32 v[72:73], v[72:73], v[128:129] op_sel_hi:[1,0]
	v_pk_mul_f32 v[78:79], v[78:79], v[128:129] op_sel_hi:[1,0]
	v_pk_mul_f32 v[76:77], v[76:77], v[128:129] op_sel_hi:[1,0]
	v_pk_mul_f32 v[82:83], v[82:83], v[128:129] op_sel_hi:[1,0]
	v_pk_mul_f32 v[80:81], v[80:81], v[128:129] op_sel_hi:[1,0]
	v_pk_mul_f32 v[86:87], v[86:87], v[128:129] op_sel_hi:[1,0]
	v_pk_mul_f32 v[84:85], v[84:85], v[128:129] op_sel_hi:[1,0]
	v_pk_mul_f32 v[98:99], v[98:99], v[128:129] op_sel_hi:[1,0]
	v_pk_mul_f32 v[96:97], v[96:97], v[128:129] op_sel_hi:[1,0]
	v_pk_mul_f32 v[110:111], v[110:111], v[128:129] op_sel_hi:[1,0]
	v_pk_mul_f32 v[108:109], v[108:109], v[128:129] op_sel_hi:[1,0]
	v_cvt_pk_bf16_f32 v128, v139, v183
	ds_read_b64_tr_b16 v[182:183], v162 offset:13824
	v_cvt_pk_bf16_f32 v129, v154, v184
	v_cvt_pk_bf16_f32 v130, v185, v186
	ds_read_b64_tr_b16 v[184:185], v162 offset:32
	v_cvt_pk_bf16_f32 v131, v187, v194
	ds_read_b64_tr_b16 v[186:187], v162 offset:4640
	ds_read_b64_tr_b16 v[198:199], v162 offset:9248
	ds_read_b64_tr_b16 v[200:201], v162 offset:13856
	ds_read_b64_tr_b16 v[202:203], v162 offset:64
	ds_read_b64_tr_b16 v[204:205], v162 offset:4672
	ds_read_b64_tr_b16 v[206:207], v162 offset:9280
	ds_read_b64_tr_b16 v[208:209], v162 offset:13888
	ds_read_b64_tr_b16 v[210:211], v162 offset:96
	ds_read_b64_tr_b16 v[212:213], v162 offset:4704
	ds_read_b64_tr_b16 v[214:215], v162 offset:9312
	ds_read_b64_tr_b16 v[216:217], v162 offset:13920
	s_andn2_b64 vcc, exec, s[6:7]
	s_waitcnt lgkmcnt(0)
	s_nop 0
	v_mfma_f32_16x16x32_bf16 v[64:67], v[140:143], v[132:135], v[64:67]
	ds_read_b64_tr_b16 v[140:141], v162 offset:128
	ds_read_b64_tr_b16 v[142:143], v162 offset:4736
	v_mfma_f32_16x16x32_bf16 v[64:67], v[180:183], v[128:131], v[64:67]
	ds_read_b64_tr_b16 v[180:181], v162 offset:9344
	ds_read_b64_tr_b16 v[182:183], v162 offset:13952
	v_mfma_f32_16x16x32_bf16 v[68:71], v[184:187], v[132:135], v[68:71]
	ds_read_b64_tr_b16 v[184:185], v162 offset:160
	ds_read_b64_tr_b16 v[186:187], v162 offset:4768
	v_mfma_f32_16x16x32_bf16 v[68:71], v[198:201], v[128:131], v[68:71]
	ds_read_b64_tr_b16 v[198:199], v162 offset:9376
	ds_read_b64_tr_b16 v[200:201], v162 offset:13984
	v_mfma_f32_16x16x32_bf16 v[72:75], v[202:205], v[132:135], v[72:75]
	ds_read_b64_tr_b16 v[202:203], v162 offset:192
	ds_read_b64_tr_b16 v[204:205], v162 offset:4800
	v_mfma_f32_16x16x32_bf16 v[72:75], v[206:209], v[128:131], v[72:75]
	ds_read_b64_tr_b16 v[206:207], v162 offset:9408
	ds_read_b64_tr_b16 v[208:209], v162 offset:14016
	v_mfma_f32_16x16x32_bf16 v[76:79], v[210:213], v[132:135], v[76:79]
	ds_read_b64_tr_b16 v[210:211], v162 offset:224
	ds_read_b64_tr_b16 v[212:213], v162 offset:4832
	v_mfma_f32_16x16x32_bf16 v[76:79], v[214:217], v[128:131], v[76:79]
	ds_read_b64_tr_b16 v[214:215], v162 offset:9440
	ds_read_b64_tr_b16 v[216:217], v162 offset:14048
	s_nop 0
	s_waitcnt lgkmcnt(0)
	s_nop 0
	v_mfma_f32_16x16x32_bf16 v[80:83], v[140:143], v[132:135], v[80:83]
	v_mfma_f32_16x16x32_bf16 v[84:87], v[184:187], v[132:135], v[84:87]
	v_mfma_f32_16x16x32_bf16 v[96:99], v[202:205], v[132:135], v[96:99]
	v_mfma_f32_16x16x32_bf16 v[108:111], v[210:213], v[132:135], v[108:111]
	v_mfma_f32_16x16x32_bf16 v[80:83], v[180:183], v[128:131], v[80:83]
	v_mfma_f32_16x16x32_bf16 v[84:87], v[198:201], v[128:131], v[84:87]
	v_mfma_f32_16x16x32_bf16 v[96:99], v[206:209], v[128:131], v[96:99]
	v_mfma_f32_16x16x32_bf16 v[108:111], v[214:217], v[128:131], v[108:111]
	s_cbranch_vccz .LBB0_259
	v_mov_b32_e32 v178, v138
	v_mov_b32_e32 v181, v136
	v_mov_b32_e32 v180, v137
	v_mov_b32_e32 v154, v179
	s_branch .LBB0_291
